# speedup vs baseline: 1.0032x; 1.0032x over previous
.LBB0_254:
	v_add_u32_e32 v188, v239, v238
	ds_read_b128 v[132:135], v188
	ds_read_b128 v[136:139], v188 offset:1024
	ds_read_b128 v[140:143], v188 offset:2048
	ds_read_b128 v[144:147], v188 offset:3072
	s_add_i32 s71, s58, s70
	v_readfirstlane_b32 s47, v241
	s_add_i32 s46, s71, 0xffffff80
	s_add_i32 vcc_lo, s85, s70
	v_readfirstlane_b32 s32, v240
	ds_read_b128 v[148:151], v237
	ds_read_b128 v[152:155], v237 offset:1024
	ds_read_b128 v[156:159], v237 offset:2048
	ds_read_b128 v[160:163], v237 offset:3072
	ds_read_b128 v[164:167], v237 offset:4096
	ds_read_b128 v[168:171], v237 offset:5120
	ds_read_b128 v[172:175], v237 offset:6144
	ds_read_b128 v[176:179], v237 offset:7168
	s_waitcnt lgkmcnt(8)
	s_barrier
	s_waitcnt lgkmcnt(0)
	s_setprio 1
	v_mfma_f32_16x16x32_bf16 v[126:129], v[132:135], v[148:151], v[126:129]
	v_mfma_f32_16x16x32_bf16 v[122:125], v[140:143], v[148:151], v[122:125]
	s_mov_b32 m0, s47
	v_mfma_f32_16x16x32_bf16 v[118:121], v[132:135], v[156:159], v[118:121]
	v_mfma_f32_16x16x32_bf16 v[114:117], v[140:143], v[156:159], v[114:117]
	buffer_load_dwordx4 v0, s[24:27], s46 offen lds
	v_mfma_f32_16x16x32_bf16 v[110:113], v[132:135], v[164:167], v[110:113]
	v_mfma_f32_16x16x32_bf16 v[106:109], v[140:143], v[164:167], v[106:109]
	s_add_i32 s46, vcc_lo, 0xffffff80
	s_mov_b32 m0, s32
	v_mfma_f32_16x16x32_bf16 v[102:105], v[132:135], v[172:175], v[102:105]
	v_mfma_f32_16x16x32_bf16 v[98:101], v[140:143], v[172:175], v[98:101]
	buffer_load_dwordx4 v0, s[24:27], s46 offen lds
	v_mfma_f32_16x16x32_bf16 v[126:129], v[136:139], v[152:155], v[126:129]
	v_mfma_f32_16x16x32_bf16 v[122:125], v[144:147], v[152:155], v[122:125]
	v_mfma_f32_16x16x32_bf16 v[118:121], v[136:139], v[160:163], v[118:121]
	v_mfma_f32_16x16x32_bf16 v[114:117], v[144:147], v[160:163], v[114:117]
	v_mfma_f32_16x16x32_bf16 v[110:113], v[136:139], v[168:171], v[110:113]
	v_mfma_f32_16x16x32_bf16 v[106:109], v[144:147], v[168:171], v[106:109]
	s_waitcnt lgkmcnt(0)
	v_mfma_f32_16x16x32_bf16 v[102:105], v[136:139], v[176:179], v[102:105]
	v_mfma_f32_16x16x32_bf16 v[98:101], v[144:147], v[176:179], v[98:101]
	s_setprio 0
	s_barrier
	v_readfirstlane_b32 s50, v236
	s_mov_b32 s46, s26
	s_mov_b32 s47, s27
	s_mov_b32 m0, s50
	v_readfirstlane_b32 s55, v235
	ds_read_b128 v[180:183], v188 offset:16384
	ds_read_b128 v[184:187], v188 offset:17408
	ds_read_b128 v[198:201], v188 offset:18432
	ds_read_b128 v[248:251], v188 offset:19456
	buffer_load_dwordx4 v0, s[44:47], s70 offen lds
	s_add_i32 s50, s8, s70
	s_mov_b32 m0, s55
	s_add_i32 s2, s2, 2
	buffer_load_dwordx4 v0, s[44:47], s50 offen lds
	s_barrier
	s_waitcnt lgkmcnt(0)
	s_setprio 1
	s_waitcnt lgkmcnt(3)
	v_mfma_f32_16x16x32_bf16 v[94:97], v[180:183], v[148:151], v[94:97]
	s_waitcnt lgkmcnt(1)
	v_mfma_f32_16x16x32_bf16 v[90:93], v[198:201], v[148:151], v[90:93]
	v_mfma_f32_16x16x32_bf16 v[86:89], v[180:183], v[156:159], v[86:89]
	v_mfma_f32_16x16x32_bf16 v[82:85], v[198:201], v[156:159], v[82:85]
	v_mfma_f32_16x16x32_bf16 v[78:81], v[180:183], v[164:167], v[78:81]
	v_mfma_f32_16x16x32_bf16 v[74:77], v[198:201], v[164:167], v[74:77]
	v_mfma_f32_16x16x32_bf16 v[70:73], v[180:183], v[172:175], v[70:73]
	v_mfma_f32_16x16x32_bf16 v[66:69], v[198:201], v[172:175], v[66:69]
	v_mfma_f32_16x16x32_bf16 v[94:97], v[184:187], v[152:155], v[94:97]
	s_waitcnt lgkmcnt(0)
	v_mfma_f32_16x16x32_bf16 v[90:93], v[248:251], v[152:155], v[90:93]
	v_mfma_f32_16x16x32_bf16 v[86:89], v[184:187], v[160:163], v[86:89]
	v_mfma_f32_16x16x32_bf16 v[82:85], v[248:251], v[160:163], v[82:85]
	v_mfma_f32_16x16x32_bf16 v[78:81], v[184:187], v[168:171], v[78:81]
	v_mfma_f32_16x16x32_bf16 v[74:77], v[248:251], v[168:171], v[74:77]
	v_mfma_f32_16x16x32_bf16 v[70:73], v[184:187], v[176:179], v[70:73]
	v_mfma_f32_16x16x32_bf16 v[66:69], v[248:251], v[176:179], v[66:69]
	s_setprio 0
	v_readfirstlane_b32 s55, v232
	s_mov_b32 m0, s55
	v_readfirstlane_b32 s55, v234
	s_barrier
	ds_read_b128 v[148:151], v237 offset:16384
	ds_read_b128 v[152:155], v237 offset:17408
	ds_read_b128 v[156:159], v237 offset:18432
	ds_read_b128 v[160:163], v237 offset:19456
	ds_read_b128 v[164:167], v237 offset:20480
	ds_read_b128 v[168:171], v237 offset:21504
	ds_read_b128 v[172:175], v237 offset:22528
	ds_read_b128 v[176:179], v237 offset:23552
	buffer_load_dwordx4 v0, s[24:27], s70 offen lds
	s_mov_b32 m0, s55
	s_nop 0
	buffer_load_dwordx4 v0, s[24:27], s50 offen lds
	s_barrier
	s_waitcnt lgkmcnt(0)
	s_setprio 1
	s_waitcnt lgkmcnt(7)
	v_mfma_f32_16x16x32_bf16 v[62:65], v[132:135], v[148:151], v[62:65]
	v_mfma_f32_16x16x32_bf16 v[58:61], v[140:143], v[148:151], v[58:61]
	s_waitcnt lgkmcnt(5)
	v_mfma_f32_16x16x32_bf16 v[54:57], v[132:135], v[156:159], v[54:57]
	v_mfma_f32_16x16x32_bf16 v[50:53], v[140:143], v[156:159], v[50:53]
	s_waitcnt lgkmcnt(3)
	v_mfma_f32_16x16x32_bf16 v[46:49], v[132:135], v[164:167], v[46:49]
	v_mfma_f32_16x16x32_bf16 v[42:45], v[140:143], v[164:167], v[42:45]
	s_waitcnt lgkmcnt(1)
	v_mfma_f32_16x16x32_bf16 v[38:41], v[132:135], v[172:175], v[38:41]
	v_mfma_f32_16x16x32_bf16 v[34:37], v[140:143], v[172:175], v[34:37]
	v_mfma_f32_16x16x32_bf16 v[62:65], v[136:139], v[152:155], v[62:65]
	v_mfma_f32_16x16x32_bf16 v[58:61], v[144:147], v[152:155], v[58:61]
	v_mfma_f32_16x16x32_bf16 v[54:57], v[136:139], v[160:163], v[54:57]
	v_mfma_f32_16x16x32_bf16 v[50:53], v[144:147], v[160:163], v[50:53]
	v_mfma_f32_16x16x32_bf16 v[46:49], v[136:139], v[168:171], v[46:49]
	v_mfma_f32_16x16x32_bf16 v[42:45], v[144:147], v[168:171], v[42:45]
	s_waitcnt lgkmcnt(0)
	v_mfma_f32_16x16x32_bf16 v[38:41], v[136:139], v[176:179], v[38:41]
	v_mfma_f32_16x16x32_bf16 v[34:37], v[144:147], v[176:179], v[34:37]
	s_setprio 0
	s_barrier
	v_readfirstlane_b32 s55, v233
	s_mov_b32 m0, s55
	v_readfirstlane_b32 s55, v231
	buffer_load_dwordx4 v0, s[44:47], s71 offen lds
	s_mov_b32 m0, s55
	s_nop 0
	buffer_load_dwordx4 v0, s[44:47], vcc_lo offen lds
	s_waitcnt vmcnt(6)
	s_barrier
	s_setprio 1
	v_mfma_f32_16x16x32_bf16 v[30:33], v[180:183], v[148:151], v[30:33]
	v_mfma_f32_16x16x32_bf16 v[26:29], v[198:201], v[148:151], v[26:29]
	v_mfma_f32_16x16x32_bf16 v[22:25], v[180:183], v[156:159], v[22:25]
	v_mfma_f32_16x16x32_bf16 v[18:21], v[198:201], v[156:159], v[18:21]
	v_mfma_f32_16x16x32_bf16 v[14:17], v[180:183], v[164:167], v[14:17]
	v_mfma_f32_16x16x32_bf16 v[10:13], v[198:201], v[164:167], v[10:13]
	v_mfma_f32_16x16x32_bf16 v[6:9], v[180:183], v[172:175], v[6:9]
	v_mfma_f32_16x16x32_bf16 v[2:5], v[198:201], v[172:175], v[2:5]
	v_mfma_f32_16x16x32_bf16 v[30:33], v[184:187], v[152:155], v[30:33]
	v_mfma_f32_16x16x32_bf16 v[26:29], v[248:251], v[152:155], v[26:29]
	v_mfma_f32_16x16x32_bf16 v[22:25], v[184:187], v[160:163], v[22:25]
	v_mfma_f32_16x16x32_bf16 v[18:21], v[248:251], v[160:163], v[18:21]
	v_mfma_f32_16x16x32_bf16 v[14:17], v[184:187], v[168:171], v[14:17]
	v_mfma_f32_16x16x32_bf16 v[10:13], v[248:251], v[168:171], v[10:13]
	v_mfma_f32_16x16x32_bf16 v[6:9], v[184:187], v[176:179], v[6:9]
	v_mfma_f32_16x16x32_bf16 v[2:5], v[248:251], v[176:179], v[2:5]
	s_setprio 0
	s_barrier
	ds_read_b128 v[132:135], v188 offset:32768
	ds_read_b128 v[136:139], v188 offset:33792
	ds_read_b128 v[140:143], v188 offset:34816
	ds_read_b128 v[144:147], v188 offset:35840
	v_readfirstlane_b32 s55, v230
	v_readfirstlane_b32 s32, v205
	ds_read_b128 v[148:151], v237 offset:32768
	ds_read_b128 v[152:155], v237 offset:33792
	ds_read_b128 v[156:159], v237 offset:34816
	ds_read_b128 v[160:163], v237 offset:35840
	ds_read_b128 v[164:167], v237 offset:36864
	ds_read_b128 v[168:171], v237 offset:37888
	ds_read_b128 v[172:175], v237 offset:38912
	ds_read_b128 v[176:179], v237 offset:39936
	s_waitcnt lgkmcnt(8)
	s_barrier
	s_waitcnt lgkmcnt(0)
	s_setprio 1
	v_mfma_f32_16x16x32_bf16 v[126:129], v[132:135], v[148:151], v[126:129]
	v_mfma_f32_16x16x32_bf16 v[122:125], v[140:143], v[148:151], v[122:125]
	s_mov_b32 m0, s55
	v_mfma_f32_16x16x32_bf16 v[118:121], v[132:135], v[156:159], v[118:121]
	v_mfma_f32_16x16x32_bf16 v[114:117], v[140:143], v[156:159], v[114:117]
	buffer_load_dwordx4 v0, s[24:27], s71 offen lds
	v_mfma_f32_16x16x32_bf16 v[110:113], v[132:135], v[164:167], v[110:113]
	v_mfma_f32_16x16x32_bf16 v[106:109], v[140:143], v[164:167], v[106:109]
	s_mov_b32 m0, s32
	v_mfma_f32_16x16x32_bf16 v[102:105], v[132:135], v[172:175], v[102:105]
	v_mfma_f32_16x16x32_bf16 v[98:101], v[140:143], v[172:175], v[98:101]
	buffer_load_dwordx4 v0, s[24:27], vcc_lo offen lds
	v_mfma_f32_16x16x32_bf16 v[126:129], v[136:139], v[152:155], v[126:129]
	v_mfma_f32_16x16x32_bf16 v[122:125], v[144:147], v[152:155], v[122:125]
	v_mfma_f32_16x16x32_bf16 v[118:121], v[136:139], v[160:163], v[118:121]
	v_mfma_f32_16x16x32_bf16 v[114:117], v[144:147], v[160:163], v[114:117]
	v_mfma_f32_16x16x32_bf16 v[110:113], v[136:139], v[168:171], v[110:113]
	v_mfma_f32_16x16x32_bf16 v[106:109], v[144:147], v[168:171], v[106:109]
	s_waitcnt lgkmcnt(0)
	v_mfma_f32_16x16x32_bf16 v[102:105], v[136:139], v[176:179], v[102:105]
	v_mfma_f32_16x16x32_bf16 v[98:101], v[144:147], v[176:179], v[98:101]
	s_setprio 0
	s_barrier
	v_readfirstlane_b32 s87, v242
	s_add_i32 s55, s70, 0x80
	s_mov_b32 m0, s87
	v_readfirstlane_b32 s87, v243
	ds_read_b128 v[180:183], v188 offset:49152
	ds_read_b128 v[184:187], v188 offset:50176
	ds_read_b128 v[198:201], v188 offset:51200
	ds_read_b128 v[248:251], v188 offset:52224
	buffer_load_dwordx4 v0, s[44:47], s55 offen lds
	s_addk_i32 s50, 0x80
	s_mov_b32 m0, s87
	s_nop 0
	buffer_load_dwordx4 v0, s[44:47], s50 offen lds
	s_barrier
	s_waitcnt lgkmcnt(0)
	s_setprio 1
	s_waitcnt lgkmcnt(3)
	v_mfma_f32_16x16x32_bf16 v[94:97], v[180:183], v[148:151], v[94:97]
	s_waitcnt lgkmcnt(1)
	v_mfma_f32_16x16x32_bf16 v[90:93], v[198:201], v[148:151], v[90:93]
	v_mfma_f32_16x16x32_bf16 v[86:89], v[180:183], v[156:159], v[86:89]
	v_mfma_f32_16x16x32_bf16 v[82:85], v[198:201], v[156:159], v[82:85]
	v_mfma_f32_16x16x32_bf16 v[78:81], v[180:183], v[164:167], v[78:81]
	v_mfma_f32_16x16x32_bf16 v[74:77], v[198:201], v[164:167], v[74:77]
	v_mfma_f32_16x16x32_bf16 v[70:73], v[180:183], v[172:175], v[70:73]
	v_mfma_f32_16x16x32_bf16 v[66:69], v[198:201], v[172:175], v[66:69]
	v_mfma_f32_16x16x32_bf16 v[94:97], v[184:187], v[152:155], v[94:97]
	s_waitcnt lgkmcnt(0)
	v_mfma_f32_16x16x32_bf16 v[90:93], v[248:251], v[152:155], v[90:93]
	v_mfma_f32_16x16x32_bf16 v[86:89], v[184:187], v[160:163], v[86:89]
	v_mfma_f32_16x16x32_bf16 v[82:85], v[248:251], v[160:163], v[82:85]
	v_mfma_f32_16x16x32_bf16 v[78:81], v[184:187], v[168:171], v[78:81]
	v_mfma_f32_16x16x32_bf16 v[74:77], v[248:251], v[168:171], v[74:77]
	v_mfma_f32_16x16x32_bf16 v[70:73], v[184:187], v[176:179], v[70:73]
	v_mfma_f32_16x16x32_bf16 v[66:69], v[248:251], v[176:179], v[66:69]
	s_setprio 0
	v_readfirstlane_b32 s87, v244
	s_mov_b32 m0, s87
	s_barrier
	ds_read_b128 v[148:151], v237 offset:49152
	ds_read_b128 v[152:155], v237 offset:50176
	ds_read_b128 v[156:159], v237 offset:51200
	ds_read_b128 v[160:163], v237 offset:52224
	ds_read_b128 v[164:167], v237 offset:53248
	ds_read_b128 v[168:171], v237 offset:54272
	ds_read_b128 v[172:175], v237 offset:55296
	ds_read_b128 v[176:179], v237 offset:56320
	buffer_load_dwordx4 v0, s[24:27], s55 offen lds
	v_readfirstlane_b32 s55, v245
	s_mov_b32 m0, s55
	s_nop 0
	buffer_load_dwordx4 v0, s[24:27], s50 offen lds
	s_barrier
	s_waitcnt lgkmcnt(0)
	s_setprio 1
	s_waitcnt lgkmcnt(7)
	v_mfma_f32_16x16x32_bf16 v[62:65], v[132:135], v[148:151], v[62:65]
	v_mfma_f32_16x16x32_bf16 v[58:61], v[140:143], v[148:151], v[58:61]
	s_waitcnt lgkmcnt(5)
	v_mfma_f32_16x16x32_bf16 v[54:57], v[132:135], v[156:159], v[54:57]
	v_mfma_f32_16x16x32_bf16 v[50:53], v[140:143], v[156:159], v[50:53]
	s_waitcnt lgkmcnt(3)
	v_mfma_f32_16x16x32_bf16 v[46:49], v[132:135], v[164:167], v[46:49]
	v_mfma_f32_16x16x32_bf16 v[42:45], v[140:143], v[164:167], v[42:45]
	s_waitcnt lgkmcnt(1)
	v_mfma_f32_16x16x32_bf16 v[38:41], v[132:135], v[172:175], v[38:41]
	v_mfma_f32_16x16x32_bf16 v[34:37], v[140:143], v[172:175], v[34:37]
	v_mfma_f32_16x16x32_bf16 v[62:65], v[136:139], v[152:155], v[62:65]
	v_mfma_f32_16x16x32_bf16 v[58:61], v[144:147], v[152:155], v[58:61]
	v_mfma_f32_16x16x32_bf16 v[54:57], v[136:139], v[160:163], v[54:57]
	v_mfma_f32_16x16x32_bf16 v[50:53], v[144:147], v[160:163], v[50:53]
	v_mfma_f32_16x16x32_bf16 v[46:49], v[136:139], v[168:171], v[46:49]
	v_mfma_f32_16x16x32_bf16 v[42:45], v[144:147], v[168:171], v[42:45]
	s_waitcnt lgkmcnt(0)
	v_mfma_f32_16x16x32_bf16 v[38:41], v[136:139], v[176:179], v[38:41]
	v_mfma_f32_16x16x32_bf16 v[34:37], v[144:147], v[176:179], v[34:37]
	s_setprio 0
	s_barrier
	v_readfirstlane_b32 s50, v246
	s_addk_i32 s71, 0x80
	s_mov_b32 m0, s50
	v_readfirstlane_b32 s50, v247
	buffer_load_dwordx4 v0, s[44:47], s71 offen lds
	s_addk_i32 vcc_lo, 0x80
	s_mov_b32 m0, s50
	s_nop 0
	buffer_load_dwordx4 v0, s[44:47], vcc_lo offen lds
	s_waitcnt vmcnt(6)
	s_barrier
	s_setprio 1
	v_mfma_f32_16x16x32_bf16 v[30:33], v[180:183], v[148:151], v[30:33]
	v_mfma_f32_16x16x32_bf16 v[26:29], v[198:201], v[148:151], v[26:29]
	v_mfma_f32_16x16x32_bf16 v[22:25], v[180:183], v[156:159], v[22:25]
	v_mfma_f32_16x16x32_bf16 v[18:21], v[198:201], v[156:159], v[18:21]
	v_mfma_f32_16x16x32_bf16 v[14:17], v[180:183], v[164:167], v[14:17]
	v_mfma_f32_16x16x32_bf16 v[10:13], v[198:201], v[164:167], v[10:13]
	v_mfma_f32_16x16x32_bf16 v[6:9], v[180:183], v[172:175], v[6:9]
	v_mfma_f32_16x16x32_bf16 v[2:5], v[198:201], v[172:175], v[2:5]
	v_mfma_f32_16x16x32_bf16 v[30:33], v[184:187], v[152:155], v[30:33]
	v_mfma_f32_16x16x32_bf16 v[26:29], v[248:251], v[152:155], v[26:29]
	v_mfma_f32_16x16x32_bf16 v[22:25], v[184:187], v[160:163], v[22:25]
	v_mfma_f32_16x16x32_bf16 v[18:21], v[248:251], v[160:163], v[18:21]
	v_mfma_f32_16x16x32_bf16 v[14:17], v[184:187], v[168:171], v[14:17]
	v_mfma_f32_16x16x32_bf16 v[10:13], v[248:251], v[168:171], v[10:13]
	v_mfma_f32_16x16x32_bf16 v[6:9], v[184:187], v[176:179], v[6:9]
	v_mfma_f32_16x16x32_bf16 v[2:5], v[248:251], v[176:179], v[2:5]
	s_setprio 0
	s_addk_i32 s70, 0x100
	s_mov_b64 s[46:47], 0x200
	s_cmp_ge_i32 s2, s59
	v_lshl_add_u64 v[130:131], v[130:131], 0, s[46:47]
	s_barrier
	s_cbranch_scc1 .LBB0_262
